# k22 + rmsnorm wave-sum butterfly via DPP (xor1,2,4,8) and v_permlane16/32_swap (xor16,32) instead of 6 ds_bpermute round trips per row
# baseline (speedup 1.0000x reference)
.Lnorm_loop:
	s_lshr_b32 s43, s4, 11
	s_lshl_b32 s43, s43, 13
	v_add_u32_e32 v156, s43, v0
	ds_read_b128 v[42:45], v156
	ds_read_b128 v[30:33], v156 offset:1024
	ds_read_b128 v[26:29], v156 offset:2048
	ds_read_b128 v[18:21], v156 offset:3072
	ds_read_b128 v[54:57], v156 offset:4096
	ds_read_b128 v[38:41], v156 offset:5120
	ds_read_b128 v[34:37], v156 offset:6144
	ds_read_b128 v[22:25], v156 offset:7168
	s_waitcnt vmcnt(28)
	v_mov_b32_e32 v50, v66
	v_mov_b32_e32 v51, v67
	v_mov_b32_e32 v52, v68
	v_mov_b32_e32 v53, v69
	v_mov_b32_e32 v62, v70
	v_mov_b32_e32 v63, v71
	v_mov_b32_e32 v64, v72
	v_mov_b32_e32 v65, v73
	v_mov_b32_e32 v58, v74
	v_mov_b32_e32 v59, v75
	v_mov_b32_e32 v60, v76
	v_mov_b32_e32 v61, v77
	v_mov_b32_e32 v46, v78
	v_mov_b32_e32 v47, v79
	v_mov_b32_e32 v48, v80
	v_mov_b32_e32 v49, v81
	s_cmp_lt_i32 s42, 0x8000
	s_cselect_b64 exec, -1, 1
	s_min_i32 s43, s42, 0x7fff
	s_lshl_b32 s43, s43, 12
	s_add_u32 s44, s40, s43
	s_addc_u32 s45, s41, 0
	global_load_dwordx4 v[66:69], v0, s[44:45] nt
	global_load_dwordx4 v[70:73], v0, s[44:45] offset:1024 nt
	global_load_dwordx4 v[74:77], v0, s[44:45] offset:2048 nt
	global_load_dwordx4 v[78:81], v0, s[44:45] offset:3072 nt
	s_mov_b64 exec, -1
	s_add_i32 s42, s42, s90
	s_waitcnt lgkmcnt(0)
	v_pk_mul_f32 v[146:147], v[52:53], v[52:53]
	v_pk_mul_f32 v[148:149], v[50:51], v[50:51]
	v_pk_mul_f32 v[142:143], v[64:65], v[64:65]
	v_pk_mul_f32 v[144:145], v[62:63], v[62:63]
	v_pk_mov_b32 v[150:151], v[148:149], v[146:147] op_sel:[1,0]
	v_mov_b32_e32 v149, v147
	v_pk_add_f32 v[146:147], v[150:151], v[148:149]
	v_pk_mov_b32 v[148:149], v[144:145], v[142:143] op_sel:[1,0]
	v_mov_b32_e32 v145, v143
	v_pk_add_f32 v[142:143], v[148:149], v[144:145]
	v_pk_add_f32 v[146:147], v[146:147], v[146:147] op_sel_hi:[0,1]
	v_pk_add_f32 v[142:143], v[142:143], v[142:143] op_sel_hi:[0,1]
	v_mul_f32_e32 v142, v58, v58
	v_pk_fma_f32 v[144:145], v[58:59], v[58:59], v[142:143] op_sel_hi:[1,1,0]
	v_mul_f32_e32 v142, v60, v60
	v_pk_fma_f32 v[148:149], v[60:61], v[60:61], v[142:143] op_sel_hi:[1,1,0]
	v_mul_f32_e32 v144, v46, v46
	v_mul_f32_e32 v148, v47, v47
	v_mul_f32_e32 v146, v48, v48
	v_mul_f32_e32 v142, v49, v49
	v_pk_add_f32 v[144:145], v[144:145], v[148:149]
	v_pk_add_f32 v[142:143], v[146:147], v[142:143]
	s_mov_b32 s0, 0xf800000
	v_pk_add_f32 v[142:143], v[144:145], v[142:143]
	v_pk_add_f32 v[56:57], v[56:57], 1.0 op_sel_hi:[1,0]
	v_add_f32_e32 v141, v142, v143
	s_nop 1
	v_mov_b32_dpp v142, v141 quad_perm:[1,0,3,2] row_mask:0xf bank_mask:0xf
	v_mov_b32_e32 v143, 0x358637bd
	v_pk_add_f32 v[54:55], v[54:55], 1.0 op_sel_hi:[1,0]
	v_pk_add_f32 v[40:41], v[40:41], 1.0 op_sel_hi:[1,0]
	v_pk_add_f32 v[38:39], v[38:39], 1.0 op_sel_hi:[1,0]
	s_waitcnt lgkmcnt(0)
	v_add_f32_e32 v141, v141, v142
	s_nop 1
	v_mov_b32_dpp v142, v141 quad_perm:[2,3,0,1] row_mask:0xf bank_mask:0xf
	v_pk_add_f32 v[36:37], v[36:37], 1.0 op_sel_hi:[1,0]
	v_pk_add_f32 v[34:35], v[34:35], 1.0 op_sel_hi:[1,0]
	v_pk_add_f32 v[24:25], v[24:25], 1.0 op_sel_hi:[1,0]
	v_pk_add_f32 v[22:23], v[22:23], 1.0 op_sel_hi:[1,0]
	s_waitcnt lgkmcnt(0)
	v_add_f32_e32 v141, v141, v142
	s_nop 1
	v_mov_b32_dpp v142, v141 row_half_mirror row_mask:0xf bank_mask:0xf
	s_nop 0
	s_nop 0
	s_nop 0
	s_nop 0
	s_waitcnt lgkmcnt(0)
	v_add_f32_e32 v141, v141, v142
	s_nop 1
	v_mov_b32_dpp v142, v141 row_mirror row_mask:0xf bank_mask:0xf
	s_nop 0
	s_nop 0
	s_nop 0
	s_nop 0
	s_waitcnt lgkmcnt(0)
	v_add_f32_e32 v141, v141, v142
	v_mov_b32_e32 v142, v141
	v_mov_b32_e32 v144, v141
	s_nop 1
	v_permlane16_swap_b32 v142, v144
	s_nop 0
	s_waitcnt lgkmcnt(0)
	v_add_f32_e32 v141, v142, v144
	v_mov_b32_e32 v142, v141
	v_mov_b32_e32 v144, v141
	s_nop 1
	v_permlane32_swap_b32 v142, v144
	s_waitcnt lgkmcnt(0)
	v_add_f32_e32 v141, v142, v144
	v_fmamk_f32 v141, v141, 0x3a800000, v143
	v_mul_f32_e32 v142, 0x4f800000, v141
	v_cmp_gt_f32_e32 vcc, s0, v141
	v_mov_b32_e32 v143, 0x260
	s_nop 0
	v_cndmask_b32_e32 v141, v141, v142, vcc
	v_sqrt_f32_e32 v142, v141
	s_nop 0
	v_add_u32_e32 v144, -1, v142
	v_add_u32_e32 v145, 1, v142
	v_fma_f32 v146, -v144, v142, v141
	v_fma_f32 v147, -v145, v142, v141
	v_cmp_ge_f32_e64 s[0:1], 0, v146
	s_nop 1
	v_cndmask_b32_e64 v142, v142, v144, s[0:1]
	v_cmp_lt_f32_e64 s[0:1], 0, v147
	s_nop 0
	s_nop 0
	v_cndmask_b32_e64 v142, v142, v145, s[0:1]
	v_mul_f32_e32 v144, 0x37800000, v142
	v_cndmask_b32_e32 v142, v142, v144, vcc
	v_cmp_class_f32_e32 vcc, v141, v143
	s_nop 1
	v_cndmask_b32_e32 v141, v142, v141, vcc
	v_div_scale_f32 v142, s[0:1], v141, v141, 1.0
	v_rcp_f32_e32 v143, v142
	v_div_scale_f32 v144, vcc, 1.0, v141, 1.0
	v_readlane_b32 s0, v253, 30
	v_fma_f32 v145, -v142, v143, 1.0
	v_fmac_f32_e32 v143, v145, v143
	v_mul_f32_e32 v145, v144, v143
	v_fma_f32 v146, -v142, v145, v144
	v_fmac_f32_e32 v145, v146, v143
	v_fma_f32 v142, -v142, v145, v144
	v_div_fmas_f32 v142, v142, v143, v145
	v_div_fixup_f32 v142, v142, v141, 1.0
	v_pk_mul_f32 v[52:53], v[52:53], v[142:143] op_sel_hi:[1,0]
	v_pk_mul_f32 v[50:51], v[50:51], v[142:143] op_sel_hi:[1,0]
	v_pk_mul_f32 v[52:53], v[4:5], v[52:53]
	v_pk_mul_f32 v[50:51], v[2:3], v[50:51]
	v_pk_fma_f32 v[44:45], v[56:57], v[52:53], v[44:45]
	v_pk_fma_f32 v[42:43], v[54:55], v[50:51], v[42:43]
	v_readlane_b32 s1, v253, 31
	v_cvt_pk_bf16_f32 v42, v42, v43
	v_cvt_pk_bf16_f32 v43, v44, v45
	global_store_dwordx2 v[114:115], v[42:43], off offset:-1024
	v_pk_mul_f32 v[42:43], v[64:65], v[142:143] op_sel_hi:[1,0]
	v_pk_mul_f32 v[44:45], v[62:63], v[142:143] op_sel_hi:[1,0]
	v_pk_mul_f32 v[42:43], v[8:9], v[42:43]
	v_pk_mul_f32 v[44:45], v[6:7], v[44:45]
	v_pk_fma_f32 v[32:33], v[40:41], v[42:43], v[32:33]
	v_pk_fma_f32 v[30:31], v[38:39], v[44:45], v[30:31]
	s_nop 0
	v_cvt_pk_bf16_f32 v30, v30, v31
	v_cvt_pk_bf16_f32 v31, v32, v33
	global_store_dwordx2 v[114:115], v[30:31], off offset:-512
	v_pk_mul_f32 v[30:31], v[60:61], v[142:143] op_sel_hi:[1,0]
	v_pk_mul_f32 v[32:33], v[58:59], v[142:143] op_sel_hi:[1,0]
	v_pk_mul_f32 v[30:31], v[12:13], v[30:31]
	v_pk_mul_f32 v[32:33], v[10:11], v[32:33]
	v_pk_fma_f32 v[28:29], v[36:37], v[30:31], v[28:29]
	v_pk_fma_f32 v[26:27], v[34:35], v[32:33], v[26:27]
	s_nop 0
	v_cvt_pk_bf16_f32 v26, v26, v27
	v_cvt_pk_bf16_f32 v27, v28, v29
	global_store_dwordx2 v[114:115], v[26:27], off
	v_pk_mul_f32 v[26:27], v[48:49], v[142:143] op_sel_hi:[1,0]
	v_pk_mul_f32 v[28:29], v[46:47], v[142:143] op_sel_hi:[1,0]
	v_pk_mul_f32 v[26:27], v[16:17], v[26:27]
	v_pk_mul_f32 v[28:29], v[14:15], v[28:29]
	v_pk_fma_f32 v[20:21], v[24:25], v[26:27], v[20:21]
	v_pk_fma_f32 v[18:19], v[22:23], v[28:29], v[18:19]
	s_nop 0
	v_cvt_pk_bf16_f32 v18, v18, v19
	v_cvt_pk_bf16_f32 v19, v20, v21
	global_store_dwordx2 v[114:115], v[18:19], off offset:512
	v_lshl_add_u64 v[114:115], v[114:115], 0, s[0:1]
	s_add_i32 s4, s4, s90
	s_cmp_lt_i32 s4, 0x8000
	s_cbranch_scc0 .Lnorm_done
	s_lshr_b32 s43, s4, 11
	s_lshl_b32 s43, s43, 13
	v_add_u32_e32 v156, s43, v0
	ds_read_b128 v[42:45], v156
	ds_read_b128 v[30:33], v156 offset:1024
	ds_read_b128 v[26:29], v156 offset:2048
	ds_read_b128 v[18:21], v156 offset:3072
	ds_read_b128 v[54:57], v156 offset:4096
	ds_read_b128 v[38:41], v156 offset:5120
	ds_read_b128 v[34:37], v156 offset:6144
	ds_read_b128 v[22:25], v156 offset:7168
	s_waitcnt vmcnt(28)
	v_mov_b32_e32 v50, v82
	v_mov_b32_e32 v51, v83
	v_mov_b32_e32 v52, v84
	v_mov_b32_e32 v53, v85
	v_mov_b32_e32 v62, v86
	v_mov_b32_e32 v63, v87
	v_mov_b32_e32 v64, v88
	v_mov_b32_e32 v65, v89
	v_mov_b32_e32 v58, v90
	v_mov_b32_e32 v59, v91
	v_mov_b32_e32 v60, v92
	v_mov_b32_e32 v61, v93
	v_mov_b32_e32 v46, v94
	v_mov_b32_e32 v47, v95
	v_mov_b32_e32 v48, v96
	v_mov_b32_e32 v49, v97
	s_cmp_lt_i32 s42, 0x8000
	s_cselect_b64 exec, -1, 1
	s_min_i32 s43, s42, 0x7fff
	s_lshl_b32 s43, s43, 12
	s_add_u32 s44, s40, s43
	s_addc_u32 s45, s41, 0
	global_load_dwordx4 v[82:85], v0, s[44:45] nt
	global_load_dwordx4 v[86:89], v0, s[44:45] offset:1024 nt
	global_load_dwordx4 v[90:93], v0, s[44:45] offset:2048 nt
	global_load_dwordx4 v[94:97], v0, s[44:45] offset:3072 nt
	s_mov_b64 exec, -1
	s_add_i32 s42, s42, s90
	s_waitcnt lgkmcnt(0)
	v_pk_mul_f32 v[146:147], v[52:53], v[52:53]
	v_pk_mul_f32 v[148:149], v[50:51], v[50:51]
	v_pk_mul_f32 v[142:143], v[64:65], v[64:65]
	v_pk_mul_f32 v[144:145], v[62:63], v[62:63]
	v_pk_mov_b32 v[150:151], v[148:149], v[146:147] op_sel:[1,0]
	v_mov_b32_e32 v149, v147
	v_pk_add_f32 v[146:147], v[150:151], v[148:149]
	v_pk_mov_b32 v[148:149], v[144:145], v[142:143] op_sel:[1,0]
	v_mov_b32_e32 v145, v143
	v_pk_add_f32 v[142:143], v[148:149], v[144:145]
	v_pk_add_f32 v[146:147], v[146:147], v[146:147] op_sel_hi:[0,1]
	v_pk_add_f32 v[142:143], v[142:143], v[142:143] op_sel_hi:[0,1]
	v_mul_f32_e32 v142, v58, v58
	v_pk_fma_f32 v[144:145], v[58:59], v[58:59], v[142:143] op_sel_hi:[1,1,0]
	v_mul_f32_e32 v142, v60, v60
	v_pk_fma_f32 v[148:149], v[60:61], v[60:61], v[142:143] op_sel_hi:[1,1,0]
	v_mul_f32_e32 v144, v46, v46
	v_mul_f32_e32 v148, v47, v47
	v_mul_f32_e32 v146, v48, v48
	v_mul_f32_e32 v142, v49, v49
	v_pk_add_f32 v[144:145], v[144:145], v[148:149]
	v_pk_add_f32 v[142:143], v[146:147], v[142:143]
	s_mov_b32 s0, 0xf800000
	v_pk_add_f32 v[142:143], v[144:145], v[142:143]
	v_pk_add_f32 v[56:57], v[56:57], 1.0 op_sel_hi:[1,0]
	v_add_f32_e32 v141, v142, v143
	s_nop 1
	v_mov_b32_dpp v142, v141 quad_perm:[1,0,3,2] row_mask:0xf bank_mask:0xf
	v_mov_b32_e32 v143, 0x358637bd
	v_pk_add_f32 v[54:55], v[54:55], 1.0 op_sel_hi:[1,0]
	v_pk_add_f32 v[40:41], v[40:41], 1.0 op_sel_hi:[1,0]
	v_pk_add_f32 v[38:39], v[38:39], 1.0 op_sel_hi:[1,0]
	s_waitcnt lgkmcnt(0)
	v_add_f32_e32 v141, v141, v142
	s_nop 1
	v_mov_b32_dpp v142, v141 quad_perm:[2,3,0,1] row_mask:0xf bank_mask:0xf
	v_pk_add_f32 v[36:37], v[36:37], 1.0 op_sel_hi:[1,0]
	v_pk_add_f32 v[34:35], v[34:35], 1.0 op_sel_hi:[1,0]
	v_pk_add_f32 v[24:25], v[24:25], 1.0 op_sel_hi:[1,0]
	v_pk_add_f32 v[22:23], v[22:23], 1.0 op_sel_hi:[1,0]
	s_waitcnt lgkmcnt(0)
	v_add_f32_e32 v141, v141, v142
	s_nop 1
	v_mov_b32_dpp v142, v141 row_half_mirror row_mask:0xf bank_mask:0xf
	s_nop 0
	s_nop 0
	s_nop 0
	s_nop 0
	s_waitcnt lgkmcnt(0)
	v_add_f32_e32 v141, v141, v142
	s_nop 1
	v_mov_b32_dpp v142, v141 row_mirror row_mask:0xf bank_mask:0xf
	s_nop 0
	s_nop 0
	s_nop 0
	s_nop 0
	s_waitcnt lgkmcnt(0)
	v_add_f32_e32 v141, v141, v142
	v_mov_b32_e32 v142, v141
	v_mov_b32_e32 v144, v141
	s_nop 1
	v_permlane16_swap_b32 v142, v144
	s_nop 0
	s_waitcnt lgkmcnt(0)
	v_add_f32_e32 v141, v142, v144
	v_mov_b32_e32 v142, v141
	v_mov_b32_e32 v144, v141
	s_nop 1
	v_permlane32_swap_b32 v142, v144
	s_waitcnt lgkmcnt(0)
	v_add_f32_e32 v141, v142, v144
	v_fmamk_f32 v141, v141, 0x3a800000, v143
	v_mul_f32_e32 v142, 0x4f800000, v141
	v_cmp_gt_f32_e32 vcc, s0, v141
	v_mov_b32_e32 v143, 0x260
	s_nop 0
	v_cndmask_b32_e32 v141, v141, v142, vcc
	v_sqrt_f32_e32 v142, v141
	s_nop 0
	v_add_u32_e32 v144, -1, v142
	v_add_u32_e32 v145, 1, v142
	v_fma_f32 v146, -v144, v142, v141
	v_fma_f32 v147, -v145, v142, v141
	v_cmp_ge_f32_e64 s[0:1], 0, v146
	s_nop 1
	v_cndmask_b32_e64 v142, v142, v144, s[0:1]
	v_cmp_lt_f32_e64 s[0:1], 0, v147
	s_nop 0
	s_nop 0
	v_cndmask_b32_e64 v142, v142, v145, s[0:1]
	v_mul_f32_e32 v144, 0x37800000, v142
	v_cndmask_b32_e32 v142, v142, v144, vcc
	v_cmp_class_f32_e32 vcc, v141, v143
	s_nop 1
	v_cndmask_b32_e32 v141, v142, v141, vcc
	v_div_scale_f32 v142, s[0:1], v141, v141, 1.0
	v_rcp_f32_e32 v143, v142
	v_div_scale_f32 v144, vcc, 1.0, v141, 1.0
	v_readlane_b32 s0, v253, 30
	v_fma_f32 v145, -v142, v143, 1.0
	v_fmac_f32_e32 v143, v145, v143
	v_mul_f32_e32 v145, v144, v143
	v_fma_f32 v146, -v142, v145, v144
	v_fmac_f32_e32 v145, v146, v143
	v_fma_f32 v142, -v142, v145, v144
	v_div_fmas_f32 v142, v142, v143, v145
	v_div_fixup_f32 v142, v142, v141, 1.0
	v_pk_mul_f32 v[52:53], v[52:53], v[142:143] op_sel_hi:[1,0]
	v_pk_mul_f32 v[50:51], v[50:51], v[142:143] op_sel_hi:[1,0]
	v_pk_mul_f32 v[52:53], v[4:5], v[52:53]
	v_pk_mul_f32 v[50:51], v[2:3], v[50:51]
	v_pk_fma_f32 v[44:45], v[56:57], v[52:53], v[44:45]
	v_pk_fma_f32 v[42:43], v[54:55], v[50:51], v[42:43]
	v_readlane_b32 s1, v253, 31
	v_cvt_pk_bf16_f32 v42, v42, v43
	v_cvt_pk_bf16_f32 v43, v44, v45
	global_store_dwordx2 v[114:115], v[42:43], off offset:-1024
	v_pk_mul_f32 v[42:43], v[64:65], v[142:143] op_sel_hi:[1,0]
	v_pk_mul_f32 v[44:45], v[62:63], v[142:143] op_sel_hi:[1,0]
	v_pk_mul_f32 v[42:43], v[8:9], v[42:43]
	v_pk_mul_f32 v[44:45], v[6:7], v[44:45]
	v_pk_fma_f32 v[32:33], v[40:41], v[42:43], v[32:33]
	v_pk_fma_f32 v[30:31], v[38:39], v[44:45], v[30:31]
	s_nop 0
	v_cvt_pk_bf16_f32 v30, v30, v31
	v_cvt_pk_bf16_f32 v31, v32, v33
	global_store_dwordx2 v[114:115], v[30:31], off offset:-512
	v_pk_mul_f32 v[30:31], v[60:61], v[142:143] op_sel_hi:[1,0]
	v_pk_mul_f32 v[32:33], v[58:59], v[142:143] op_sel_hi:[1,0]
	v_pk_mul_f32 v[30:31], v[12:13], v[30:31]
	v_pk_mul_f32 v[32:33], v[10:11], v[32:33]
	v_pk_fma_f32 v[28:29], v[36:37], v[30:31], v[28:29]
	v_pk_fma_f32 v[26:27], v[34:35], v[32:33], v[26:27]
	s_nop 0
	v_cvt_pk_bf16_f32 v26, v26, v27
	v_cvt_pk_bf16_f32 v27, v28, v29
	global_store_dwordx2 v[114:115], v[26:27], off
	v_pk_mul_f32 v[26:27], v[48:49], v[142:143] op_sel_hi:[1,0]
	v_pk_mul_f32 v[28:29], v[46:47], v[142:143] op_sel_hi:[1,0]
	v_pk_mul_f32 v[26:27], v[16:17], v[26:27]
	v_pk_mul_f32 v[28:29], v[14:15], v[28:29]
	v_pk_fma_f32 v[20:21], v[24:25], v[26:27], v[20:21]
	v_pk_fma_f32 v[18:19], v[22:23], v[28:29], v[18:19]
	s_nop 0
	v_cvt_pk_bf16_f32 v18, v18, v19
	v_cvt_pk_bf16_f32 v19, v20, v21
	global_store_dwordx2 v[114:115], v[18:19], off offset:512
	v_lshl_add_u64 v[114:115], v[114:115], 0, s[0:1]
	s_add_i32 s4, s4, s90
	s_cmp_lt_i32 s4, 0x8000
	s_cbranch_scc0 .Lnorm_done
	s_lshr_b32 s43, s4, 11
	s_lshl_b32 s43, s43, 13
	v_add_u32_e32 v156, s43, v0
	ds_read_b128 v[42:45], v156
	ds_read_b128 v[30:33], v156 offset:1024
	ds_read_b128 v[26:29], v156 offset:2048
	ds_read_b128 v[18:21], v156 offset:3072
	ds_read_b128 v[54:57], v156 offset:4096
	ds_read_b128 v[38:41], v156 offset:5120
	ds_read_b128 v[34:37], v156 offset:6144
	ds_read_b128 v[22:25], v156 offset:7168
	s_waitcnt vmcnt(28)
	v_mov_b32_e32 v50, v98
	v_mov_b32_e32 v51, v99
	v_mov_b32_e32 v52, v100
	v_mov_b32_e32 v53, v101
	v_mov_b32_e32 v62, v102
	v_mov_b32_e32 v63, v103
	v_mov_b32_e32 v64, v104
	v_mov_b32_e32 v65, v105
	v_mov_b32_e32 v58, v106
	v_mov_b32_e32 v59, v107
	v_mov_b32_e32 v60, v108
	v_mov_b32_e32 v61, v109
	v_mov_b32_e32 v46, v110
	v_mov_b32_e32 v47, v111
	v_mov_b32_e32 v48, v112
	v_mov_b32_e32 v49, v113
	s_cmp_lt_i32 s42, 0x8000
	s_cselect_b64 exec, -1, 1
	s_min_i32 s43, s42, 0x7fff
	s_lshl_b32 s43, s43, 12
	s_add_u32 s44, s40, s43
	s_addc_u32 s45, s41, 0
	global_load_dwordx4 v[98:101], v0, s[44:45] nt
	global_load_dwordx4 v[102:105], v0, s[44:45] offset:1024 nt
	global_load_dwordx4 v[106:109], v0, s[44:45] offset:2048 nt
	global_load_dwordx4 v[110:113], v0, s[44:45] offset:3072 nt
	s_mov_b64 exec, -1
	s_add_i32 s42, s42, s90
	s_waitcnt lgkmcnt(0)
	v_pk_mul_f32 v[146:147], v[52:53], v[52:53]
	v_pk_mul_f32 v[148:149], v[50:51], v[50:51]
	v_pk_mul_f32 v[142:143], v[64:65], v[64:65]
	v_pk_mul_f32 v[144:145], v[62:63], v[62:63]
	v_pk_mov_b32 v[150:151], v[148:149], v[146:147] op_sel:[1,0]
	v_mov_b32_e32 v149, v147
	v_pk_add_f32 v[146:147], v[150:151], v[148:149]
	v_pk_mov_b32 v[148:149], v[144:145], v[142:143] op_sel:[1,0]
	v_mov_b32_e32 v145, v143
	v_pk_add_f32 v[142:143], v[148:149], v[144:145]
	v_pk_add_f32 v[146:147], v[146:147], v[146:147] op_sel_hi:[0,1]
	v_pk_add_f32 v[142:143], v[142:143], v[142:143] op_sel_hi:[0,1]
	v_mul_f32_e32 v142, v58, v58
	v_pk_fma_f32 v[144:145], v[58:59], v[58:59], v[142:143] op_sel_hi:[1,1,0]
	v_mul_f32_e32 v142, v60, v60
	v_pk_fma_f32 v[148:149], v[60:61], v[60:61], v[142:143] op_sel_hi:[1,1,0]
	v_mul_f32_e32 v144, v46, v46
	v_mul_f32_e32 v148, v47, v47
	v_mul_f32_e32 v146, v48, v48
	v_mul_f32_e32 v142, v49, v49
	v_pk_add_f32 v[144:145], v[144:145], v[148:149]
	v_pk_add_f32 v[142:143], v[146:147], v[142:143]
	s_mov_b32 s0, 0xf800000
	v_pk_add_f32 v[142:143], v[144:145], v[142:143]
	v_pk_add_f32 v[56:57], v[56:57], 1.0 op_sel_hi:[1,0]
	v_add_f32_e32 v141, v142, v143
	s_nop 1
	v_mov_b32_dpp v142, v141 quad_perm:[1,0,3,2] row_mask:0xf bank_mask:0xf
	v_mov_b32_e32 v143, 0x358637bd
	v_pk_add_f32 v[54:55], v[54:55], 1.0 op_sel_hi:[1,0]
	v_pk_add_f32 v[40:41], v[40:41], 1.0 op_sel_hi:[1,0]
	v_pk_add_f32 v[38:39], v[38:39], 1.0 op_sel_hi:[1,0]
	s_waitcnt lgkmcnt(0)
	v_add_f32_e32 v141, v141, v142
	s_nop 1
	v_mov_b32_dpp v142, v141 quad_perm:[2,3,0,1] row_mask:0xf bank_mask:0xf
	v_pk_add_f32 v[36:37], v[36:37], 1.0 op_sel_hi:[1,0]
	v_pk_add_f32 v[34:35], v[34:35], 1.0 op_sel_hi:[1,0]
	v_pk_add_f32 v[24:25], v[24:25], 1.0 op_sel_hi:[1,0]
	v_pk_add_f32 v[22:23], v[22:23], 1.0 op_sel_hi:[1,0]
	s_waitcnt lgkmcnt(0)
	v_add_f32_e32 v141, v141, v142
	s_nop 1
	v_mov_b32_dpp v142, v141 row_half_mirror row_mask:0xf bank_mask:0xf
	s_nop 0
	s_nop 0
	s_nop 0
	s_nop 0
	s_waitcnt lgkmcnt(0)
	v_add_f32_e32 v141, v141, v142
	s_nop 1
	v_mov_b32_dpp v142, v141 row_mirror row_mask:0xf bank_mask:0xf
	s_nop 0
	s_nop 0
	s_nop 0
	s_nop 0
	s_waitcnt lgkmcnt(0)
	v_add_f32_e32 v141, v141, v142
	v_mov_b32_e32 v142, v141
	v_mov_b32_e32 v144, v141
	s_nop 1
	v_permlane16_swap_b32 v142, v144
	s_nop 0
	s_waitcnt lgkmcnt(0)
	v_add_f32_e32 v141, v142, v144
	v_mov_b32_e32 v142, v141
	v_mov_b32_e32 v144, v141
	s_nop 1
	v_permlane32_swap_b32 v142, v144
	s_waitcnt lgkmcnt(0)
	v_add_f32_e32 v141, v142, v144
	v_fmamk_f32 v141, v141, 0x3a800000, v143
	v_mul_f32_e32 v142, 0x4f800000, v141
	v_cmp_gt_f32_e32 vcc, s0, v141
	v_mov_b32_e32 v143, 0x260
	s_nop 0
	v_cndmask_b32_e32 v141, v141, v142, vcc
	v_sqrt_f32_e32 v142, v141
	s_nop 0
	v_add_u32_e32 v144, -1, v142
	v_add_u32_e32 v145, 1, v142
	v_fma_f32 v146, -v144, v142, v141
	v_fma_f32 v147, -v145, v142, v141
	v_cmp_ge_f32_e64 s[0:1], 0, v146
	s_nop 1
	v_cndmask_b32_e64 v142, v142, v144, s[0:1]
	v_cmp_lt_f32_e64 s[0:1], 0, v147
	s_nop 0
	s_nop 0
	v_cndmask_b32_e64 v142, v142, v145, s[0:1]
	v_mul_f32_e32 v144, 0x37800000, v142
	v_cndmask_b32_e32 v142, v142, v144, vcc
	v_cmp_class_f32_e32 vcc, v141, v143
	s_nop 1
	v_cndmask_b32_e32 v141, v142, v141, vcc
	v_div_scale_f32 v142, s[0:1], v141, v141, 1.0
	v_rcp_f32_e32 v143, v142
	v_div_scale_f32 v144, vcc, 1.0, v141, 1.0
	v_readlane_b32 s0, v253, 30
	v_fma_f32 v145, -v142, v143, 1.0
	v_fmac_f32_e32 v143, v145, v143
	v_mul_f32_e32 v145, v144, v143
	v_fma_f32 v146, -v142, v145, v144
	v_fmac_f32_e32 v145, v146, v143
	v_fma_f32 v142, -v142, v145, v144
	v_div_fmas_f32 v142, v142, v143, v145
	v_div_fixup_f32 v142, v142, v141, 1.0
	v_pk_mul_f32 v[52:53], v[52:53], v[142:143] op_sel_hi:[1,0]
	v_pk_mul_f32 v[50:51], v[50:51], v[142:143] op_sel_hi:[1,0]
	v_pk_mul_f32 v[52:53], v[4:5], v[52:53]
	v_pk_mul_f32 v[50:51], v[2:3], v[50:51]
	v_pk_fma_f32 v[44:45], v[56:57], v[52:53], v[44:45]
	v_pk_fma_f32 v[42:43], v[54:55], v[50:51], v[42:43]
	v_readlane_b32 s1, v253, 31
	v_cvt_pk_bf16_f32 v42, v42, v43
	v_cvt_pk_bf16_f32 v43, v44, v45
	global_store_dwordx2 v[114:115], v[42:43], off offset:-1024
	v_pk_mul_f32 v[42:43], v[64:65], v[142:143] op_sel_hi:[1,0]
	v_pk_mul_f32 v[44:45], v[62:63], v[142:143] op_sel_hi:[1,0]
	v_pk_mul_f32 v[42:43], v[8:9], v[42:43]
	v_pk_mul_f32 v[44:45], v[6:7], v[44:45]
	v_pk_fma_f32 v[32:33], v[40:41], v[42:43], v[32:33]
	v_pk_fma_f32 v[30:31], v[38:39], v[44:45], v[30:31]
	s_nop 0
	v_cvt_pk_bf16_f32 v30, v30, v31
	v_cvt_pk_bf16_f32 v31, v32, v33
	global_store_dwordx2 v[114:115], v[30:31], off offset:-512
	v_pk_mul_f32 v[30:31], v[60:61], v[142:143] op_sel_hi:[1,0]
	v_pk_mul_f32 v[32:33], v[58:59], v[142:143] op_sel_hi:[1,0]
	v_pk_mul_f32 v[30:31], v[12:13], v[30:31]
	v_pk_mul_f32 v[32:33], v[10:11], v[32:33]
	v_pk_fma_f32 v[28:29], v[36:37], v[30:31], v[28:29]
	v_pk_fma_f32 v[26:27], v[34:35], v[32:33], v[26:27]
	s_nop 0
	v_cvt_pk_bf16_f32 v26, v26, v27
	v_cvt_pk_bf16_f32 v27, v28, v29
	global_store_dwordx2 v[114:115], v[26:27], off
	v_pk_mul_f32 v[26:27], v[48:49], v[142:143] op_sel_hi:[1,0]
	v_pk_mul_f32 v[28:29], v[46:47], v[142:143] op_sel_hi:[1,0]
	v_pk_mul_f32 v[26:27], v[16:17], v[26:27]
	v_pk_mul_f32 v[28:29], v[14:15], v[28:29]
	v_pk_fma_f32 v[20:21], v[24:25], v[26:27], v[20:21]
	v_pk_fma_f32 v[18:19], v[22:23], v[28:29], v[18:19]
	s_nop 0
	v_cvt_pk_bf16_f32 v18, v18, v19
	v_cvt_pk_bf16_f32 v19, v20, v21
	global_store_dwordx2 v[114:115], v[18:19], off offset:512
	v_lshl_add_u64 v[114:115], v[114:115], 0, s[0:1]
	s_add_i32 s4, s4, s90
	s_cmp_lt_i32 s4, 0x8000
	s_cbranch_scc0 .Lnorm_done
	s_lshr_b32 s43, s4, 11
	s_lshl_b32 s43, s43, 13
	v_add_u32_e32 v156, s43, v0
	ds_read_b128 v[42:45], v156
	ds_read_b128 v[30:33], v156 offset:1024
	ds_read_b128 v[26:29], v156 offset:2048
	ds_read_b128 v[18:21], v156 offset:3072
	ds_read_b128 v[54:57], v156 offset:4096
	ds_read_b128 v[38:41], v156 offset:5120
	ds_read_b128 v[34:37], v156 offset:6144
	ds_read_b128 v[22:25], v156 offset:7168
	s_waitcnt vmcnt(28)
	v_mov_b32_e32 v50, v118
	v_mov_b32_e32 v51, v119
	v_mov_b32_e32 v52, v120
	v_mov_b32_e32 v53, v121
	v_mov_b32_e32 v62, v122
	v_mov_b32_e32 v63, v123
	v_mov_b32_e32 v64, v124
	v_mov_b32_e32 v65, v125
	v_mov_b32_e32 v58, v126
	v_mov_b32_e32 v59, v127
	v_mov_b32_e32 v60, v128
	v_mov_b32_e32 v61, v129
	v_mov_b32_e32 v46, v130
	v_mov_b32_e32 v47, v131
	v_mov_b32_e32 v48, v132
	v_mov_b32_e32 v49, v133
	s_cmp_lt_i32 s42, 0x8000
	s_cselect_b64 exec, -1, 1
	s_min_i32 s43, s42, 0x7fff
	s_lshl_b32 s43, s43, 12
	s_add_u32 s44, s40, s43
	s_addc_u32 s45, s41, 0
	global_load_dwordx4 v[118:121], v0, s[44:45] nt
	global_load_dwordx4 v[122:125], v0, s[44:45] offset:1024 nt
	global_load_dwordx4 v[126:129], v0, s[44:45] offset:2048 nt
	global_load_dwordx4 v[130:133], v0, s[44:45] offset:3072 nt
	s_mov_b64 exec, -1
	s_add_i32 s42, s42, s90
	s_waitcnt lgkmcnt(0)
	v_pk_mul_f32 v[146:147], v[52:53], v[52:53]
	v_pk_mul_f32 v[148:149], v[50:51], v[50:51]
	v_pk_mul_f32 v[142:143], v[64:65], v[64:65]
	v_pk_mul_f32 v[144:145], v[62:63], v[62:63]
	v_pk_mov_b32 v[150:151], v[148:149], v[146:147] op_sel:[1,0]
	v_mov_b32_e32 v149, v147
	v_pk_add_f32 v[146:147], v[150:151], v[148:149]
	v_pk_mov_b32 v[148:149], v[144:145], v[142:143] op_sel:[1,0]
	v_mov_b32_e32 v145, v143
	v_pk_add_f32 v[142:143], v[148:149], v[144:145]
	v_pk_add_f32 v[146:147], v[146:147], v[146:147] op_sel_hi:[0,1]
	v_pk_add_f32 v[142:143], v[142:143], v[142:143] op_sel_hi:[0,1]
	v_mul_f32_e32 v142, v58, v58
	v_pk_fma_f32 v[144:145], v[58:59], v[58:59], v[142:143] op_sel_hi:[1,1,0]
	v_mul_f32_e32 v142, v60, v60
	v_pk_fma_f32 v[148:149], v[60:61], v[60:61], v[142:143] op_sel_hi:[1,1,0]
	v_mul_f32_e32 v144, v46, v46
	v_mul_f32_e32 v148, v47, v47
	v_mul_f32_e32 v146, v48, v48
	v_mul_f32_e32 v142, v49, v49
	v_pk_add_f32 v[144:145], v[144:145], v[148:149]
	v_pk_add_f32 v[142:143], v[146:147], v[142:143]
	s_mov_b32 s0, 0xf800000
	v_pk_add_f32 v[142:143], v[144:145], v[142:143]
	v_pk_add_f32 v[56:57], v[56:57], 1.0 op_sel_hi:[1,0]
	v_add_f32_e32 v141, v142, v143
	s_nop 1
	v_mov_b32_dpp v142, v141 quad_perm:[1,0,3,2] row_mask:0xf bank_mask:0xf
	v_mov_b32_e32 v143, 0x358637bd
	v_pk_add_f32 v[54:55], v[54:55], 1.0 op_sel_hi:[1,0]
	v_pk_add_f32 v[40:41], v[40:41], 1.0 op_sel_hi:[1,0]
	v_pk_add_f32 v[38:39], v[38:39], 1.0 op_sel_hi:[1,0]
	s_waitcnt lgkmcnt(0)
	v_add_f32_e32 v141, v141, v142
	s_nop 1
	v_mov_b32_dpp v142, v141 quad_perm:[2,3,0,1] row_mask:0xf bank_mask:0xf
	v_pk_add_f32 v[36:37], v[36:37], 1.0 op_sel_hi:[1,0]
	v_pk_add_f32 v[34:35], v[34:35], 1.0 op_sel_hi:[1,0]
	v_pk_add_f32 v[24:25], v[24:25], 1.0 op_sel_hi:[1,0]
	v_pk_add_f32 v[22:23], v[22:23], 1.0 op_sel_hi:[1,0]
	s_waitcnt lgkmcnt(0)
	v_add_f32_e32 v141, v141, v142
	s_nop 1
	v_mov_b32_dpp v142, v141 row_half_mirror row_mask:0xf bank_mask:0xf
	s_nop 0
	s_nop 0
	s_nop 0
	s_nop 0
	s_waitcnt lgkmcnt(0)
	v_add_f32_e32 v141, v141, v142
	s_nop 1
	v_mov_b32_dpp v142, v141 row_mirror row_mask:0xf bank_mask:0xf
	s_nop 0
	s_nop 0
	s_nop 0
	s_nop 0
	s_waitcnt lgkmcnt(0)
	v_add_f32_e32 v141, v141, v142
	v_mov_b32_e32 v142, v141
	v_mov_b32_e32 v144, v141
	s_nop 1
	v_permlane16_swap_b32 v142, v144
	s_nop 0
	s_waitcnt lgkmcnt(0)
	v_add_f32_e32 v141, v142, v144
	v_mov_b32_e32 v142, v141
	v_mov_b32_e32 v144, v141
	s_nop 1
	v_permlane32_swap_b32 v142, v144
	s_waitcnt lgkmcnt(0)
	v_add_f32_e32 v141, v142, v144
	v_fmamk_f32 v141, v141, 0x3a800000, v143
	v_mul_f32_e32 v142, 0x4f800000, v141
	v_cmp_gt_f32_e32 vcc, s0, v141
	v_mov_b32_e32 v143, 0x260
	s_nop 0
	v_cndmask_b32_e32 v141, v141, v142, vcc
	v_sqrt_f32_e32 v142, v141
	s_nop 0
	v_add_u32_e32 v144, -1, v142
	v_add_u32_e32 v145, 1, v142
	v_fma_f32 v146, -v144, v142, v141
	v_fma_f32 v147, -v145, v142, v141
	v_cmp_ge_f32_e64 s[0:1], 0, v146
	s_nop 1
	v_cndmask_b32_e64 v142, v142, v144, s[0:1]
	v_cmp_lt_f32_e64 s[0:1], 0, v147
	s_nop 0
	s_nop 0
	v_cndmask_b32_e64 v142, v142, v145, s[0:1]
	v_mul_f32_e32 v144, 0x37800000, v142
	v_cndmask_b32_e32 v142, v142, v144, vcc
	v_cmp_class_f32_e32 vcc, v141, v143
	s_nop 1
	v_cndmask_b32_e32 v141, v142, v141, vcc
	v_div_scale_f32 v142, s[0:1], v141, v141, 1.0
	v_rcp_f32_e32 v143, v142
	v_div_scale_f32 v144, vcc, 1.0, v141, 1.0
	v_readlane_b32 s0, v253, 30
	v_fma_f32 v145, -v142, v143, 1.0
	v_fmac_f32_e32 v143, v145, v143
	v_mul_f32_e32 v145, v144, v143
	v_fma_f32 v146, -v142, v145, v144
	v_fmac_f32_e32 v145, v146, v143
	v_fma_f32 v142, -v142, v145, v144
	v_div_fmas_f32 v142, v142, v143, v145
	v_div_fixup_f32 v142, v142, v141, 1.0
	v_pk_mul_f32 v[52:53], v[52:53], v[142:143] op_sel_hi:[1,0]
	v_pk_mul_f32 v[50:51], v[50:51], v[142:143] op_sel_hi:[1,0]
	v_pk_mul_f32 v[52:53], v[4:5], v[52:53]
	v_pk_mul_f32 v[50:51], v[2:3], v[50:51]
	v_pk_fma_f32 v[44:45], v[56:57], v[52:53], v[44:45]
	v_pk_fma_f32 v[42:43], v[54:55], v[50:51], v[42:43]
	v_readlane_b32 s1, v253, 31
	v_cvt_pk_bf16_f32 v42, v42, v43
	v_cvt_pk_bf16_f32 v43, v44, v45
	global_store_dwordx2 v[114:115], v[42:43], off offset:-1024
	v_pk_mul_f32 v[42:43], v[64:65], v[142:143] op_sel_hi:[1,0]
	v_pk_mul_f32 v[44:45], v[62:63], v[142:143] op_sel_hi:[1,0]
	v_pk_mul_f32 v[42:43], v[8:9], v[42:43]
	v_pk_mul_f32 v[44:45], v[6:7], v[44:45]
	v_pk_fma_f32 v[32:33], v[40:41], v[42:43], v[32:33]
	v_pk_fma_f32 v[30:31], v[38:39], v[44:45], v[30:31]
	s_nop 0
	v_cvt_pk_bf16_f32 v30, v30, v31
	v_cvt_pk_bf16_f32 v31, v32, v33
	global_store_dwordx2 v[114:115], v[30:31], off offset:-512
	v_pk_mul_f32 v[30:31], v[60:61], v[142:143] op_sel_hi:[1,0]
	v_pk_mul_f32 v[32:33], v[58:59], v[142:143] op_sel_hi:[1,0]
	v_pk_mul_f32 v[30:31], v[12:13], v[30:31]
	v_pk_mul_f32 v[32:33], v[10:11], v[32:33]
	v_pk_fma_f32 v[28:29], v[36:37], v[30:31], v[28:29]
	v_pk_fma_f32 v[26:27], v[34:35], v[32:33], v[26:27]
	s_nop 0
	v_cvt_pk_bf16_f32 v26, v26, v27
	v_cvt_pk_bf16_f32 v27, v28, v29
	global_store_dwordx2 v[114:115], v[26:27], off
	v_pk_mul_f32 v[26:27], v[48:49], v[142:143] op_sel_hi:[1,0]
	v_pk_mul_f32 v[28:29], v[46:47], v[142:143] op_sel_hi:[1,0]
	v_pk_mul_f32 v[26:27], v[16:17], v[26:27]
	v_pk_mul_f32 v[28:29], v[14:15], v[28:29]
	v_pk_fma_f32 v[20:21], v[24:25], v[26:27], v[20:21]
	v_pk_fma_f32 v[18:19], v[22:23], v[28:29], v[18:19]
	s_nop 0
	v_cvt_pk_bf16_f32 v18, v18, v19
	v_cvt_pk_bf16_f32 v19, v20, v21
	global_store_dwordx2 v[114:115], v[18:19], off offset:512
	v_lshl_add_u64 v[114:115], v[114:115], 0, s[0:1]
	s_add_i32 s4, s4, s90
	s_cmp_lt_i32 s4, 0x8000
	s_cbranch_scc0 .Lnorm_done
	s_branch .Lnorm_loop
